# x2 + attention main loop: one static s_setprio 1 for waves 4-7 (strategy 4)
# baseline (speedup 1.0000x reference)
; #define LAS __attribute__((address_space(3)))
; __device__ __forceinline__ int v_st(int k, int c) { const int kk = (k & ~0xC) | ((k & 4) << 1) | ((k & 8) >> 1); return ((kk >> 3) * 4 + (c >> 5)) * 512 + ((kk & 7) * 32 + (c & 31)) * 2; }
; __device__ __forceinline__ void qkt(f32x16& p0, f32x16& p1, const LAS unsigned char* Ks, const bf16x8* qr, const LAS unsigned char* qrp, int qsw, const int (&kq)[4], int hi) {
;     p0 = f32x16{}; p1 = f32x16{};
; #pragma unroll
;     for (int d0 = 0; d0 < 12; ++d0) {
;         const bf16x8 b0 = *(const LAS bf16x8*)(Ks + kq[d0 & 3] + 128 * (d0 >> 2));
;         const bf16x8 b1 = *(const LAS bf16x8*)(Ks + kq[d0 & 3] + 128 * (d0 >> 2) + 32 * 384);
;         bf16x8 qv; if (d0 < 8) qv = qr[d0]; else qv = *(const LAS bf16x8*)(qrp + (((2 * (d0 - 8) + hi) ^ qsw) << 4));
;         p0 = __builtin_amdgcn_mfma_f32_32x32x16_bf16(b0, qv, p0, 0, 0, 0);
;         p1 = __builtin_amdgcn_mfma_f32_32x32x16_bf16(b1, qv, p1, 0, 0, 0); }
; }
; template <bool DIRECT> ...
;     ...
;     const bf16_t* Qw = QKV + (size_t)(qrow0 + wid * QBLK + r32) * NUP + h * 192 + hi * 8;
; #pragma unroll
;     for (int d0 = 0; d0 < 8; ++d0) qr[d0] = *(const bf16x8*)(Qw + d0 * 16);
;     LAS unsigned char* qrp = lds + OFF_QR + wid * 4096 + r32 * 128; const int qsw = (r32 >> 1) & 7;
;     int kq[4];
; #pragma unroll
;     for (int q = 0; q < 4; ++q) kq[q] = 384 * r32 + (((2 * q + hi) ^ qsw) << 4);
; #pragma unroll
;     for (int d0 = 8; d0 < 12; ++d0) *(LAS bf16x8*)(qrp + (((2 * (d0 - 8) + hi) ^ qsw) << 4)) = *(const bf16x8*)(Qw + d0 * 16);
;     const int sr = tid >> 4, sc = (tid & 15) * 8;
;     const int vst0 = v_st(sr, sc);
;     const int kst0 = KSWZ(sr, sc * 2);
;     const int krst = KSWZ(tid >> 3, 256 + (tid & 7) * 16);
;     const unsigned voffV = (unsigned)(sr * NUP + sc) * 2u, voffR = (unsigned)((tid >> 3) * INWP + (tid & 7) * 8) * 2u;
;     const char* Vb = (const char*)(QKV + 768 + h * 256 + 128); const char* Kb = (const char*)(QKV + 768 + h * 256); const char* Rb = (const char*)(Z + ZKR);
;     const int vb0 = (int)(uintptr_t)V_lds + v_rd_base(lane);
;     bf16x8 vs0, vs1, ks0, ks1, ks2;
;     ...
;     f32x16 pA0, pA1, pB0, pB1; float mnA, mnB, alA, alB; bf16x8 pa0, pa1, pa2, pa3;
;     SLOAD(0); SWAIT(); SWRITE(0); __syncthreads();
;     qkt(pA0, pA1, K_lds, qr, qrp, qsw, kq, hi); partialSM(pA0, pA1, m_reg, mnA, alA);
.LBB0_835:
	s_bfe_u32 s19, s55, 0x10002
	s_bfe_u32 s56, s55, 0x10003
	s_lshl_b32 s18, s19, 12
	s_lshl_b32 s19, s19, 8
	s_bitset1_b32 s19, 13
	s_mul_i32 s20, s56, 0x880
	s_add_i32 s21, s20, s19
	s_or_b32 s24, s20, s18
	s_or_b32 s23, s21, 64
	s_addk_i32 s21, 0x80
	s_add_i32 s22, s24, 0xffffff80
	s_cmp_eq_u32 s56, 0
	s_cselect_b32 s22, s21, s22
	s_addk_i32 s24, 0xff40
	s_cmp_eq_u32 s56, 0
	s_cselect_b32 s23, s23, s24
	s_add_i32 s21, s18, 0xffffff00
	s_cmp_eq_u32 s56, 0
	s_cselect_b32 s26, s19, s21
	s_lshl_b32 s24, s55, 4
	s_and_b32 s24, s24, 0xffffff00
	s_add_i32 s24, s18, s24
	v_add_u32_e32 v196, s24, v178
	s_and_b32 s57, s55, 3
	v_or_b32_e32 v162, v196, v154
	v_mov_b64_e32 v[0:1], s[44:45]
	v_mad_i64_i32 v[0:1], s[24:25], v162, s13, v[0:1]
	s_mul_i32 s76, s57, 0x180
	v_lshl_add_u64 v[0:1], v[0:1], 0, s[76:77]
	v_mov_b32_e32 v161, v97
	v_lshl_add_u64 v[4:5], v[0:1], 0, v[160:161]
	global_load_dwordx4 v[126:129], v[4:5], off
	global_load_dwordx4 v[122:125], v[4:5], off offset:32
	global_load_dwordx4 v[118:121], v[4:5], off offset:64
	global_load_dwordx4 v[114:117], v[4:5], off offset:96
	global_load_dwordx4 v[110:113], v[4:5], off offset:128
	global_load_dwordx4 v[106:109], v[4:5], off offset:160
	global_load_dwordx4 v[102:105], v[4:5], off offset:192
	global_load_dwordx4 v[98:101], v[4:5], off offset:224
	global_load_dwordx4 v[0:3], v[4:5], off offset:256
	v_add_u32_e32 v207, v187, v179
	v_add_u32_e32 v206, v187, v181
	v_add_u32_e32 v197, v187, v183
	s_lshl_b32 s24, s57, 9
	s_add_u32 s40, s53, s24
	s_addc_u32 s41, s54, 0
	s_add_i32 s26, s26, s20
	s_mul_i32 s24, s26, 0xe00
	s_mul_hi_i32 s25, s26, 0xe00
	s_add_u32 s24, s40, s24
	s_addc_u32 s25, s41, s25
	v_lshl_add_u64 v[8:9], s[24:25], 0, v[156:157]
	s_mov_b32 s27, 0x1c000
	v_add_u32_e32 v161, v187, v185
	v_add_co_u32_e32 v12, vcc, s27, v8
	v_mad_i64_i32 v[16:17], s[24:25], s26, v218, v[158:159]
	s_nop 0
	v_addc_co_u32_e32 v13, vcc, 0, v9, vcc
	v_add_u32_e32 v209, 0, v180
	v_add_u32_e32 v211, 0, v182
	v_add_u32_e32 v210, 0, v184
	v_add_u32_e32 v208, 0, v186
	s_mul_i32 s24, s23, 0xe00
	s_mul_hi_i32 s25, s23, 0xe00
	s_mov_b32 s76, s77
	s_mov_b32 s78, s77
	s_mov_b32 s79, s77
	s_mov_b32 s80, s77
	s_mov_b32 s81, s77
	s_mov_b32 s82, s77
	s_mov_b32 s83, s77
	s_mov_b32 s84, s77
	s_mov_b32 s85, s77
	s_mov_b32 s86, s77
	s_mov_b32 s87, s77
	s_mov_b32 s88, s77
	s_mov_b32 s89, s77
	s_mov_b32 s90, s77
	s_mov_b32 s91, s77
	v_ashrrev_i32_e32 v163, 31, v162
	s_mov_b32 s58, 1
	v_lshl_add_u64 v[164:165], s[40:41], 0, v[156:157]
	v_mov_b32_e32 v212, 0
	s_waitcnt vmcnt(0)
	ds_write_b128 v207, v[0:3]
	global_load_dwordx4 v[0:3], v[4:5], off offset:288
	s_waitcnt vmcnt(0)
	ds_write_b128 v206, v[0:3]
	global_load_dwordx4 v[0:3], v[4:5], off offset:320
	s_waitcnt vmcnt(0)
	ds_write_b128 v197, v[0:3]
	global_load_dwordx4 v[0:3], v[4:5], off offset:352
	s_waitcnt vmcnt(0)
	ds_write_b128 v161, v[0:3]
	global_load_dwordx4 v[0:3], v[8:9], off offset:256
	global_load_dwordx4 v[4:7], v[12:13], off offset:256
	s_nop 0
	global_load_dwordx4 v[8:11], v[8:9], off
	s_nop 0
	global_load_dwordx4 v[12:15], v[12:13], off
	s_nop 0
	global_load_dwordx4 v[16:19], v[16:17], off
	s_waitcnt vmcnt(0)
	s_waitcnt vmcnt(4)
	ds_write_b128 v191, v[0:3]
	s_waitcnt vmcnt(3)
	ds_write_b128 v191, v[4:7] offset:8192
	v_add_u32_e32 v0, 0, v188
	s_waitcnt vmcnt(2)
	ds_write_b128 v0, v[8:11] offset:49152
	s_waitcnt vmcnt(1)
	ds_write_b128 v0, v[12:15] offset:61440
	v_add_u32_e32 v0, 0, v189
	s_waitcnt vmcnt(0)
	ds_write_b128 v0, v[16:19] offset:49152
	s_waitcnt lgkmcnt(0)
	s_barrier
	ds_read_b128 v[16:19], v209 offset:49152
	ds_read_b128 v[20:23], v209 offset:61440
	s_waitcnt lgkmcnt(1)
	v_mfma_f32_32x32x16_bf16 v[32:47], v[16:19], v[126:129], 0
	ds_read_b128 v[48:51], v211 offset:49152
	ds_read_b128 v[52:55], v211 offset:61440
	v_mov_b64_e32 v[0:1], s[76:77]
	v_mov_b64_e32 v[14:15], s[90:91]
	v_mov_b64_e32 v[2:3], s[78:79]
	v_mov_b64_e32 v[4:5], s[80:81]
	v_mov_b64_e32 v[6:7], s[82:83]
	v_mov_b64_e32 v[8:9], s[84:85]
	s_waitcnt lgkmcnt(2)
	v_mfma_f32_32x32x16_bf16 v[16:31], v[20:23], v[126:129], 0
	v_mov_b64_e32 v[10:11], s[86:87]
	v_mov_b64_e32 v[12:13], s[88:89]
	s_waitcnt lgkmcnt(1)
	v_mfma_f32_32x32x16_bf16 v[32:47], v[48:51], v[122:125], v[32:47]
	s_waitcnt lgkmcnt(0)
	v_mfma_f32_32x32x16_bf16 v[16:31], v[52:55], v[122:125], v[16:31]
	ds_read_b128 v[48:51], v210 offset:49152
	ds_read_b128 v[52:55], v210 offset:61440
	s_waitcnt lgkmcnt(1)
	v_mfma_f32_32x32x16_bf16 v[32:47], v[48:51], v[118:121], v[32:47]
	s_waitcnt lgkmcnt(0)
	v_mfma_f32_32x32x16_bf16 v[16:31], v[52:55], v[118:121], v[16:31]
	ds_read_b128 v[48:51], v208 offset:49152
	ds_read_b128 v[52:55], v208 offset:61440
	s_waitcnt lgkmcnt(1)
	v_mfma_f32_32x32x16_bf16 v[32:47], v[48:51], v[114:117], v[32:47]
	s_waitcnt lgkmcnt(0)
	v_mfma_f32_32x32x16_bf16 v[16:31], v[52:55], v[114:117], v[16:31]
	ds_read_b128 v[48:51], v209 offset:49280
	ds_read_b128 v[52:55], v209 offset:61568
	s_waitcnt lgkmcnt(1)
	v_mfma_f32_32x32x16_bf16 v[32:47], v[48:51], v[110:113], v[32:47]
	s_waitcnt lgkmcnt(0)
	v_mfma_f32_32x32x16_bf16 v[16:31], v[52:55], v[110:113], v[16:31]
	ds_read_b128 v[48:51], v211 offset:49280
	ds_read_b128 v[52:55], v211 offset:61568
	s_waitcnt lgkmcnt(1)
	v_mfma_f32_32x32x16_bf16 v[32:47], v[48:51], v[106:109], v[32:47]
	s_waitcnt lgkmcnt(0)
	v_mfma_f32_32x32x16_bf16 v[16:31], v[52:55], v[106:109], v[16:31]
	ds_read_b128 v[48:51], v210 offset:49280
	ds_read_b128 v[52:55], v210 offset:61568
	s_waitcnt lgkmcnt(1)
	v_mfma_f32_32x32x16_bf16 v[32:47], v[48:51], v[102:105], v[32:47]
	s_waitcnt lgkmcnt(0)
	v_mfma_f32_32x32x16_bf16 v[16:31], v[52:55], v[102:105], v[16:31]
	ds_read_b128 v[48:51], v208 offset:49280
	ds_read_b128 v[52:55], v208 offset:61568
	s_waitcnt lgkmcnt(1)
; #define SLOAD(kt) do { SLOADV(kt); SLOADK(kt); } while (0)
; #define SWRITE(b) do { *(LAS bf16x8*)(V_lds + (b) * SHM_V + vst0) = vs0; *(LAS bf16x8*)(V_lds + (b) * SHM_V + vst0 + 8192) = vs1; \
;     *(LAS bf16x8*)(K_lds + (b) * SHM_K + kst0) = ks0; *(LAS bf16x8*)(K_lds + (b) * SHM_K + kst0 + 32 * 384) = ks1; *(LAS bf16x8*)(K_lds + (b) * SHM_K + krst) = ks2; } while (0)
; #define SWAIT() asm volatile("s_waitcnt vmcnt(0)" ::: "memory")
; __device__ __forceinline__ void partialSM(f32x16& p0, f32x16& p1, float& m_reg, float& mn, float& alpha) {
;     constexpr float C = SCALE * 1.4426950408889634f;
;     float pmax = p0[0];
; #pragma unroll
;     for (int r = 1; r < 16; ++r) pmax = fmaxf(pmax, p0[r]);
; #pragma unroll
;     for (int r = 0; r < 16; ++r) pmax = fmaxf(pmax, p1[r]);
;     { auto rr = __builtin_amdgcn_permlane32_swap(__float_as_uint(pmax), __float_as_uint(pmax), false, false);
;       pmax = fmaxf(__uint_as_float(rr[0]), __uint_as_float(rr[1])); }
;     if (__builtin_expect(__all(pmax - m_reg <= THR / SCALE), 1)) { mn = m_reg; alpha = 1.f; }
;     else { mn = fmaxf(m_reg, pmax); alpha = __builtin_amdgcn_exp2f((m_reg - mn) * C); m_reg = mn; }
;     const float mnC = -mn * C;
; #pragma unroll
;     for (int r = 0; r < 16; ++r) p0[r] = fmaf(p0[r], C, mnC);
; #pragma unroll
;     for (int r = 0; r < 16; ++r) p1[r] = fmaf(p1[r], C, mnC);
; #pragma unroll
;     for (int r = 0; r < 16; ++r) p0[r] = __builtin_amdgcn_exp2f(p0[r]);
; }
; template <bool DIRECT> ...
;     ...
;     SLOAD(0); SWAIT(); SWRITE(0); __syncthreads();
;     qkt(pA0, pA1, K_lds, qr, qrp, qsw, kq, hi); partialSM(pA0, pA1, m_reg, mnA, alA);
;     SLOAD(1);
;     SWAIT(); SWRITE(1); __syncthreads();
;     if (2 < NT) SLOAD(2);
;     int kb = 1;
	v_mfma_f32_32x32x16_bf16 v[32:47], v[48:51], v[98:101], v[32:47]
	s_waitcnt lgkmcnt(0)
	v_mfma_f32_32x32x16_bf16 v[16:31], v[52:55], v[98:101], v[16:31]
	ds_read_b128 v[48:51], v209 offset:49408
	ds_read_b128 v[52:55], v209 offset:61696
	ds_read_b128 v[56:59], v207
	s_waitcnt lgkmcnt(0)
	v_mfma_f32_32x32x16_bf16 v[32:47], v[48:51], v[56:59], v[32:47]
	v_mfma_f32_32x32x16_bf16 v[16:31], v[52:55], v[56:59], v[16:31]
	ds_read_b128 v[48:51], v211 offset:49408
	ds_read_b128 v[52:55], v211 offset:61696
	ds_read_b128 v[56:59], v206
	s_waitcnt lgkmcnt(0)
	v_mfma_f32_32x32x16_bf16 v[32:47], v[48:51], v[56:59], v[32:47]
	v_mfma_f32_32x32x16_bf16 v[16:31], v[52:55], v[56:59], v[16:31]
	ds_read_b128 v[48:51], v210 offset:49408
	ds_read_b128 v[52:55], v210 offset:61696
	ds_read_b128 v[56:59], v197
	s_waitcnt lgkmcnt(0)
	v_mfma_f32_32x32x16_bf16 v[32:47], v[48:51], v[56:59], v[32:47]
	v_mfma_f32_32x32x16_bf16 v[16:31], v[52:55], v[56:59], v[16:31]
	ds_read_b128 v[48:51], v208 offset:49408
	ds_read_b128 v[52:55], v208 offset:61696
	ds_read_b128 v[56:59], v161
	s_waitcnt lgkmcnt(0)
	v_mfma_f32_32x32x16_bf16 v[32:47], v[48:51], v[56:59], v[32:47]
	v_mfma_f32_32x32x16_bf16 v[16:31], v[52:55], v[56:59], v[16:31]
	s_nop 10
	v_max_f32_e32 v48, v33, v33
	v_max_f32_e32 v49, v32, v32
	v_max_f32_e32 v48, v49, v48
	v_max3_f32 v48, v48, v34, v35
	v_max3_f32 v48, v48, v36, v37
	v_max3_f32 v48, v48, v38, v39
	v_max3_f32 v48, v48, v40, v41
	v_max3_f32 v48, v48, v42, v43
	v_max3_f32 v48, v48, v44, v45
	v_max3_f32 v48, v48, v46, v47
	v_max3_f32 v48, v48, v16, v17
	v_max3_f32 v48, v48, v18, v19
	v_max3_f32 v48, v48, v20, v21
	v_max3_f32 v48, v48, v22, v23
	v_max3_f32 v48, v48, v24, v25
	v_max3_f32 v48, v48, v26, v27
	v_max3_f32 v48, v48, v28, v29
	v_max3_f32 v48, v48, v30, v31
	v_mov_b32_e32 v49, v48
	s_nop 1
	v_permlane32_swap_b32_e32 v48, v49
	v_max_f32_e32 v49, v49, v49
	v_max_f32_e32 v48, v48, v48
	v_max_f32_e32 v48, v48, v49
	v_add_f32_e32 v49, 0x7149f2ca, v48
	v_max_f32_e32 v48, 0xf149f2ca, v48
	v_cmp_ge_f32_e32 vcc, s14, v49
	v_sub_f32_e32 v49, 0xf149f2ca, v48
	v_mul_f32_e32 v49, 0x3dd53b94, v49
	s_cmp_eq_u64 vcc, exec
	v_exp_f32_e32 v49, v49
	s_cselect_b64 vcc, -1, 0
	v_cndmask_b32_e32 v221, v48, v219, vcc
	v_mul_f32_e32 v48, 0xbdd53b94, v221
	v_cndmask_b32_e64 v213, v49, 1.0, vcc
	v_mov_b32_e32 v49, v48
	s_add_u32 s24, s40, s24
	v_fmac_f32_e32 v49, 0x3dd53b94, v47
	s_addc_u32 s25, s41, s25
	v_pk_fma_f32 v[168:169], v[24:25], s[8:9], v[48:49] op_sel_hi:[1,0,0]
	v_lshl_add_u64 v[24:25], s[24:25], 0, v[156:157]
	v_pk_fma_f32 v[152:153], v[28:29], s[8:9], v[48:49] op_sel_hi:[1,0,0]
	v_add_co_u32_e32 v28, vcc, s27, v24
	v_pk_fma_f32 v[174:175], v[18:19], s[8:9], v[48:49] op_sel_hi:[1,0,0]
	v_pk_fma_f32 v[176:177], v[16:17], s[8:9], v[48:49] op_sel_hi:[1,0,0]
	global_load_dwordx4 v[16:19], v[24:25], off offset:256
	v_addc_co_u32_e32 v29, vcc, 0, v25, vcc
	v_fmamk_f32 v32, v32, 0x3dd53b94, v48
	v_fmamk_f32 v33, v33, 0x3dd53b94, v48
	v_pk_fma_f32 v[150:151], v[30:31], s[8:9], v[48:49] op_sel_hi:[1,0,0]
	v_pk_fma_f32 v[166:167], v[26:27], s[8:9], v[48:49] op_sel_hi:[1,0,0]
	v_pk_fma_f32 v[170:171], v[22:23], s[8:9], v[48:49] op_sel_hi:[1,0,0]
	v_pk_fma_f32 v[172:173], v[20:21], s[8:9], v[48:49] op_sel_hi:[1,0,0]
	global_load_dwordx4 v[20:23], v[28:29], off offset:256
	s_nop 0
	global_load_dwordx4 v[24:27], v[24:25], off
	s_nop 0
	global_load_dwordx4 v[28:31], v[28:29], off
	v_fmamk_f32 v34, v34, 0x3dd53b94, v48
	v_fmamk_f32 v35, v35, 0x3dd53b94, v48
	v_exp_f32_e32 v235, v32
	v_exp_f32_e32 v237, v33
	v_mad_i64_i32 v[32:33], s[24:25], s23, v218, v[158:159]
	v_exp_f32_e32 v233, v34
	v_exp_f32_e32 v236, v35
	global_load_dwordx4 v[32:35], v[32:33], off
	s_add_i32 s23, 0, 0x12000
	s_waitcnt vmcnt(0)
	s_waitcnt vmcnt(4)
	ds_write_b128 v191, v[16:19] offset:16384
	s_waitcnt vmcnt(3)
	ds_write_b128 v191, v[20:23] offset:24576
	v_add_u32_e32 v16, s23, v188
	s_mul_i32 s24, s22, 0xe00
	s_waitcnt vmcnt(2)
	ds_write_b128 v16, v[24:27]
	s_waitcnt vmcnt(1)
	ds_write_b128 v16, v[28:31] offset:12288
	v_add_u32_e32 v16, s23, v189
	s_mul_hi_i32 s23, s22, 0xe00
	s_add_u32 s24, s40, s24
	s_addc_u32 s25, s41, s23
	v_mad_i64_i32 v[20:21], s[22:23], s22, v218, v[158:159]
	v_fmamk_f32 v36, v36, 0x3dd53b94, v48
	s_waitcnt vmcnt(0)
	ds_write_b128 v16, v[32:35]
	v_lshl_add_u64 v[16:17], s[24:25], 0, v[156:157]
	v_add_co_u32_e32 v18, vcc, s27, v16
	s_waitcnt lgkmcnt(0)
	s_nop 0
	v_addc_co_u32_e32 v19, vcc, 0, v17, vcc
	s_barrier
	global_load_dwordx4 v[130:133], v[16:17], off offset:256
	global_load_dwordx4 v[134:137], v[18:19], off offset:256
	global_load_dwordx4 v[138:141], v[20:21], off
	global_load_dwordx4 v[146:149], v[18:19], off
	global_load_dwordx4 v[142:145], v[16:17], off
	v_fmamk_f32 v37, v37, 0x3dd53b94, v48
	v_fmamk_f32 v38, v38, 0x3dd53b94, v48
	v_fmamk_f32 v39, v39, 0x3dd53b94, v48
	v_fmamk_f32 v40, v40, 0x3dd53b94, v48
	v_fmamk_f32 v41, v41, 0x3dd53b94, v48
	v_fmamk_f32 v42, v42, 0x3dd53b94, v48
	v_fmamk_f32 v43, v43, 0x3dd53b94, v48
	v_fmamk_f32 v44, v44, 0x3dd53b94, v48
	v_fmamk_f32 v45, v45, 0x3dd53b94, v48
	v_fmamk_f32 v46, v46, 0x3dd53b94, v48
	v_exp_f32_e32 v232, v36
	v_exp_f32_e32 v234, v37
	v_exp_f32_e32 v230, v38
	v_exp_f32_e32 v231, v39
	v_exp_f32_e32 v227, v40
	v_exp_f32_e32 v229, v41
	v_exp_f32_e32 v226, v42
	v_exp_f32_e32 v228, v43
	v_exp_f32_e32 v223, v44
	v_exp_f32_e32 v225, v45
	v_exp_f32_e32 v222, v46
	v_exp_f32_e32 v224, v49
	v_mov_b64_e32 v[62:63], v[14:15]
	v_mov_b64_e32 v[46:47], v[14:15]
	v_mov_b64_e32 v[30:31], v[14:15]
	v_mov_b64_e32 v[60:61], v[12:13]
	v_mov_b64_e32 v[58:59], v[10:11]
	v_mov_b64_e32 v[56:57], v[8:9]
	v_mov_b64_e32 v[54:55], v[6:7]
	v_mov_b64_e32 v[52:53], v[4:5]
	v_mov_b64_e32 v[50:51], v[2:3]
	v_mov_b64_e32 v[48:49], v[0:1]
	v_mov_b64_e32 v[44:45], v[12:13]
	v_mov_b64_e32 v[42:43], v[10:11]
	v_mov_b64_e32 v[40:41], v[8:9]
	v_mov_b64_e32 v[38:39], v[6:7]
	v_mov_b64_e32 v[36:37], v[4:5]
	v_mov_b64_e32 v[34:35], v[2:3]
	v_mov_b64_e32 v[32:33], v[0:1]
	v_mov_b64_e32 v[28:29], v[12:13]
	v_mov_b64_e32 v[26:27], v[10:11]
	v_mov_b64_e32 v[24:25], v[8:9]
	v_mov_b64_e32 v[22:23], v[6:7]
	v_mov_b64_e32 v[20:21], v[4:5]
	v_mov_b64_e32 v[18:19], v[2:3]
	v_mov_b64_e32 v[16:17], v[0:1]
	s_mov_b32 s22, 1
	v_readlane_b32 s29, v253, 10
	s_nop 3
	s_cmp_lt_u32 s29, 0x100
	s_cbranch_scc1 .Latt_prio_skip
	s_setprio 1
; #define LAS __attribute__((address_space(3)))
; #define SBAR() __builtin_amdgcn_sched_barrier(0)
; __device__ __forceinline__ void finishSM(f32x16& p0, f32x16& p1, float alpha, float& l_reg, bf16x8& pa0, bf16x8& pa1, bf16x8& pa2, bf16x8& pa3) {
; #pragma unroll
;     for (int r = 0; r < 16; ++r) p1[r] = __builtin_amdgcn_exp2f(p1[r]);
;     float ps = 0;
; #pragma unroll
;     for (int r = 0; r < 16; ++r) ps += p0[r];
; #pragma unroll
;     for (int r = 0; r < 16; ++r) ps += p1[r];
;     { auto rr = __builtin_amdgcn_permlane32_swap(__float_as_uint(ps), __float_as_uint(ps), false, false);
;       ps = __uint_as_float(rr[0]) + __uint_as_float(rr[1]); }
;     l_reg = l_reg * alpha + ps;
;     ...
;     PK4(p0, 0, pa0); PK4(p0, 8, pa1); PK4(p1, 0, pa2); PK4(p1, 8, pa3);
;     ...
; }
; __device__ __forceinline__ void qkt(f32x16& p0, f32x16& p1, const LAS unsigned char* Ks, const bf16x8* qr, const LAS unsigned char* qrp, int qsw, const int (&kq)[4], int hi) {
;     p0 = f32x16{}; p1 = f32x16{};
; #pragma unroll
;     for (int d0 = 0; d0 < 12; ++d0) {
;         const bf16x8 b0 = *(const LAS bf16x8*)(Ks + kq[d0 & 3] + 128 * (d0 >> 2));
;         const bf16x8 b1 = *(const LAS bf16x8*)(Ks + kq[d0 & 3] + 128 * (d0 >> 2) + 32 * 384);
;         bf16x8 qv; if (d0 < 8) qv = qr[d0]; else qv = *(const LAS bf16x8*)(qrp + (((2 * (d0 - 8) + hi) ^ qsw) << 4));
;         p0 = __builtin_amdgcn_mfma_f32_32x32x16_bf16(b0, qv, p0, 0, 0, 0);
;         p1 = __builtin_amdgcn_mfma_f32_32x32x16_bf16(b1, qv, p1, 0, 0, 0); }
; }
; template <bool DIRECT> ...
;     ...
;         { const int pb_ = kb == 0 ? 2 : kb - 1, nb_ = kb == 2 ? 0 : kb + 1;
;         SBAR(); qkt(pB0, pB1, K_lds + kb * SHM_K, qr, qrp, qsw, kq, hi);
;         finishSM(pA0, pA1, alA, l_reg, pa0, pa1, pa2, pa3); SBAR();
;         pv_d0(o, vb0 + pb_ * SHM_V, pa0, pa1, pa2, pa3); partialSM(pB0, pB1, m_reg, mnB, alB);
.Latt_prio_skip:
.LBB0_836:
	s_add_i32 s23, s58, 1
	s_cmp_lg_u32 s58, 2
	s_cselect_b32 s23, s23, 0
	s_mul_i32 s24, s58, 0x6000
	s_add_i32 s24, s24, 0
	v_add_u32_e32 v96, s24, v180
	ds_read_b128 v[64:67], v96 offset:49152
	ds_read_b128 v[68:71], v96 offset:61440
	v_add_u32_e32 v200, s24, v182
	ds_read_b128 v[238:241], v200 offset:49152
	ds_read_b128 v[242:245], v200 offset:61440
	v_add_u32_e32 v201, s24, v184
	s_waitcnt lgkmcnt(3)
	v_mfma_f32_32x32x16_bf16 v[80:95], v[64:67], v[126:129], 0
	v_add_u32_e32 v202, s24, v186
	v_exp_f32_e32 v174, v174
	v_exp_f32_e32 v175, v175
	v_exp_f32_e32 v203, v168
	s_waitcnt lgkmcnt(2)
	v_mfma_f32_32x32x16_bf16 v[64:79], v[68:71], v[126:129], 0
	s_waitcnt lgkmcnt(0)
	v_mfma_f32_32x32x16_bf16 v[64:79], v[242:245], v[122:125], v[64:79]
	v_mfma_f32_32x32x16_bf16 v[80:95], v[238:241], v[122:125], v[80:95]
	ds_read_b128 v[238:241], v201 offset:49152
	ds_read_b128 v[242:245], v201 offset:61440
	s_waitcnt lgkmcnt(0)
	v_mfma_f32_32x32x16_bf16 v[64:79], v[242:245], v[118:121], v[64:79]
	v_mfma_f32_32x32x16_bf16 v[80:95], v[238:241], v[118:121], v[80:95]
	ds_read_b128 v[238:241], v202 offset:49152
	ds_read_b128 v[242:245], v202 offset:61440
	s_waitcnt lgkmcnt(0)
	v_mfma_f32_32x32x16_bf16 v[64:79], v[242:245], v[114:117], v[64:79]
	v_mfma_f32_32x32x16_bf16 v[80:95], v[238:241], v[114:117], v[80:95]
	ds_read_b128 v[238:241], v96 offset:49280
	ds_read_b128 v[242:245], v96 offset:61568
	s_waitcnt lgkmcnt(0)
	v_mfma_f32_32x32x16_bf16 v[64:79], v[242:245], v[110:113], v[64:79]
	v_mfma_f32_32x32x16_bf16 v[80:95], v[238:241], v[110:113], v[80:95]
	ds_read_b128 v[238:241], v200 offset:49280
	ds_read_b128 v[242:245], v200 offset:61568
	s_waitcnt lgkmcnt(0)
	v_mfma_f32_32x32x16_bf16 v[64:79], v[242:245], v[106:109], v[64:79]
	v_mfma_f32_32x32x16_bf16 v[80:95], v[238:241], v[106:109], v[80:95]
	ds_read_b128 v[238:241], v201 offset:49280
	ds_read_b128 v[242:245], v201 offset:61568
	s_waitcnt lgkmcnt(0)
	v_mfma_f32_32x32x16_bf16 v[64:79], v[242:245], v[102:105], v[64:79]
	v_mfma_f32_32x32x16_bf16 v[80:95], v[238:241], v[102:105], v[80:95]
	ds_read_b128 v[238:241], v202 offset:49280
	ds_read_b128 v[242:245], v202 offset:61568
	s_waitcnt lgkmcnt(0)
	v_mfma_f32_32x32x16_bf16 v[64:79], v[242:245], v[98:101], v[64:79]
	v_mfma_f32_32x32x16_bf16 v[80:95], v[238:241], v[98:101], v[80:95]
	ds_read_b128 v[238:241], v96 offset:49408
	ds_read_b128 v[242:245], v96 offset:61696
	ds_read_b128 v[246:249], v207
	v_exp_f32_e32 v96, v176
	v_exp_f32_e32 v176, v177
	v_exp_f32_e32 v177, v172
	s_waitcnt lgkmcnt(0)
	v_mfma_f32_32x32x16_bf16 v[64:79], v[242:245], v[246:249], v[64:79]
	v_mfma_f32_32x32x16_bf16 v[80:95], v[238:241], v[246:249], v[80:95]
	ds_read_b128 v[238:241], v200 offset:49408
	ds_read_b128 v[242:245], v200 offset:61696
	ds_read_b128 v[246:249], v206
	v_exp_f32_e32 v200, v173
	s_waitcnt lgkmcnt(0)
	v_mfma_f32_32x32x16_bf16 v[64:79], v[242:245], v[246:249], v[64:79]
	v_mfma_f32_32x32x16_bf16 v[80:95], v[238:241], v[246:249], v[80:95]
	ds_read_b128 v[238:241], v201 offset:49408
	ds_read_b128 v[242:245], v201 offset:61696
	ds_read_b128 v[246:249], v197
	v_exp_f32_e32 v201, v170
	s_waitcnt lgkmcnt(0)
	v_mfma_f32_32x32x16_bf16 v[64:79], v[242:245], v[246:249], v[64:79]
	v_mfma_f32_32x32x16_bf16 v[80:95], v[238:241], v[246:249], v[80:95]
	ds_read_b128 v[238:241], v202 offset:49408
	ds_read_b128 v[242:245], v202 offset:61696
	ds_read_b128 v[246:249], v161
	v_exp_f32_e32 v202, v171
	s_waitcnt lgkmcnt(0)
	v_mfma_f32_32x32x16_bf16 v[64:79], v[242:245], v[246:249], v[64:79]
	v_exp_f32_e32 v243, v150
	v_add_f32_e32 v150, 0, v235
	v_add_f32_e32 v150, v237, v150
	v_add_f32_e32 v150, v233, v150
	v_add_f32_e32 v150, v236, v150
	v_add_f32_e32 v150, v232, v150
	v_add_f32_e32 v150, v234, v150
	v_add_f32_e32 v150, v230, v150
	v_add_f32_e32 v150, v231, v150
	v_add_f32_e32 v150, v227, v150
	v_add_f32_e32 v150, v229, v150
	v_add_f32_e32 v150, v226, v150
	v_add_f32_e32 v150, v228, v150
	v_add_f32_e32 v150, v223, v150
	v_add_f32_e32 v150, v225, v150
	v_add_f32_e32 v150, v222, v150
	v_add_f32_e32 v150, v224, v150
	v_add_f32_e32 v150, v96, v150
	v_add_f32_e32 v150, v176, v150
	v_add_f32_e32 v150, v174, v150
	v_add_f32_e32 v150, v175, v150
	v_add_f32_e32 v150, v177, v150
	v_mfma_f32_32x32x16_bf16 v[80:95], v[238:241], v[246:249], v[80:95]
	v_exp_f32_e32 v238, v169
	v_add_f32_e32 v150, v200, v150
	v_exp_f32_e32 v239, v166
	v_add_f32_e32 v150, v201, v150
	v_exp_f32_e32 v240, v167
	v_add_f32_e32 v150, v202, v150
	v_exp_f32_e32 v241, v152
	v_add_f32_e32 v150, v203, v150
	v_exp_f32_e32 v242, v153
	v_add_f32_e32 v150, v238, v150
	v_add_f32_e32 v150, v239, v150
	v_exp_f32_e32 v244, v151
	v_add_f32_e32 v150, v240, v150
	v_add_f32_e32 v150, v241, v150
	v_add_f32_e32 v150, v242, v150
	v_add_f32_e32 v150, v243, v150
	v_add_f32_e32 v166, v244, v150
	v_mov_b32_e32 v167, v166
	v_cvt_pk_bf16_f32 v150, v235, v237
	v_cvt_pk_bf16_f32 v151, v233, v236
	v_cvt_pk_bf16_f32 v152, v232, v234
	s_nop 1
	v_permlane32_swap_b32_e32 v166, v167
	v_cvt_pk_bf16_f32 v153, v230, v231
	v_permlane32_swap_b32_e32 v150, v152
	v_cvt_pk_bf16_f32 v168, v227, v229
	v_cvt_pk_bf16_f32 v169, v226, v228
	v_cvt_pk_bf16_f32 v170, v223, v225
	v_cvt_pk_bf16_f32 v171, v222, v224
	v_cvt_pk_bf16_f32 v172, v96, v176
	v_cvt_pk_bf16_f32 v173, v174, v175
	v_cvt_pk_bf16_f32 v174, v177, v200
	v_cvt_pk_bf16_f32 v175, v201, v202
	v_cvt_pk_bf16_f32 v222, v203, v238
	v_cvt_pk_bf16_f32 v223, v239, v240
	v_cvt_pk_bf16_f32 v224, v241, v242
	v_cvt_pk_bf16_f32 v225, v243, v244
	v_permlane32_swap_b32_e32 v151, v153
	v_permlane32_swap_b32_e32 v168, v170
	v_permlane32_swap_b32_e32 v169, v171
	v_permlane32_swap_b32_e32 v172, v174
	v_permlane32_swap_b32_e32 v173, v175
	v_permlane32_swap_b32_e32 v222, v224
	v_permlane32_swap_b32_e32 v223, v225
	s_lshl_b32 s24, s58, 14
	s_addk_i32 s24, 0xc000
	s_cmp_lg_u32 s58, 0
	s_cselect_b32 s24, s24, 0x8000
	v_add_u32_e32 v96, s24, v190
	ds_read_b64_tr_b16 v[226:227], v96 offset:0
	ds_read_b64_tr_b16 v[228:229], v96 offset:0x800
	ds_read_b64_tr_b16 v[230:231], v96 offset:0x1000
	ds_read_b64_tr_b16 v[232:233], v96 offset:0x1800
	ds_read_b64_tr_b16 v[234:235], v96 offset:0x2000
	ds_read_b64_tr_b16 v[236:237], v96 offset:0x2800
	ds_read_b64_tr_b16 v[238:239], v96 offset:0x3000
	ds_read_b64_tr_b16 v[240:241], v96 offset:0x3800
	s_waitcnt lgkmcnt(0)
; #define SBAR() __builtin_amdgcn_sched_barrier(0)
; #define SLOAD(kt) do { SLOADV(kt); SLOADK(kt); } while (0)
; #define SWAIT() asm volatile("s_waitcnt vmcnt(0)" ::: "memory")
; __device__ __forceinline__ void partialSM(f32x16& p0, f32x16& p1, float& m_reg, float& mn, float& alpha) {
;     constexpr float C = SCALE * 1.4426950408889634f;
;     float pmax = p0[0];
; #pragma unroll
;     for (int r = 1; r < 16; ++r) pmax = fmaxf(pmax, p0[r]);
; #pragma unroll
;     for (int r = 0; r < 16; ++r) pmax = fmaxf(pmax, p1[r]);
;     { auto rr = __builtin_amdgcn_permlane32_swap(__float_as_uint(pmax), __float_as_uint(pmax), false, false);
;       pmax = fmaxf(__uint_as_float(rr[0]), __uint_as_float(rr[1])); }
;     if (__builtin_expect(__all(pmax - m_reg <= THR / SCALE), 1)) { mn = m_reg; alpha = 1.f; }
;     else { mn = fmaxf(m_reg, pmax); alpha = __builtin_amdgcn_exp2f((m_reg - mn) * C); m_reg = mn; }
; template <int D0> __device__ __forceinline__ void pv_one(f32x16& od, int vb, bf16x8 pa0, bf16x8 pa1, bf16x8 pa2, bf16x8 pa3) {
;     const s16x4 l0 = tr_read<v_rd_off(D0, 0, 0)>(vb), h0 = tr_read<v_rd_off(D0, 0, 1)>(vb), l1 = tr_read<v_rd_off(D0, 1, 0)>(vb), h1 = tr_read<v_rd_off(D0, 1, 1)>(vb);
;     const s16x4 l2 = tr_read<v_rd_off(D0, 2, 0)>(vb), h2 = tr_read<v_rd_off(D0, 2, 1)>(vb), l3 = tr_read<v_rd_off(D0, 3, 0)>(vb), h3 = tr_read<v_rd_off(D0, 3, 1)>(vb);
;     asm volatile("s_waitcnt lgkmcnt(0)" ::: "memory"); SBAR();
;     ...
;     od = __builtin_amdgcn_mfma_f32_32x32x16_bf16(pa0, PK(l0, h0), od, 0, 0, 0);
;     od = __builtin_amdgcn_mfma_f32_32x32x16_bf16(pa1, PK(l1, h1), od, 0, 0, 0);
;     od = __builtin_amdgcn_mfma_f32_32x32x16_bf16(pa2, PK(l2, h2), od, 0, 0, 0);
;     od = __builtin_amdgcn_mfma_f32_32x32x16_bf16(pa3, PK(l3, h3), od, 0, 0, 0);
;     ...
; }
; __device__ __forceinline__ void pv_d0(f32x16* o, int vb, bf16x8 pa0, bf16x8 pa1, bf16x8 pa2, bf16x8 pa3) {
;     pv_one<0>(o[0], vb, pa0, pa1, pa2, pa3); pv_one<1>(o[1], vb, pa0, pa1, pa2, pa3); pv_one<2>(o[2], vb, pa0, pa1, pa2, pa3); pv_one<3>(o[3], vb, pa0, pa1, pa2, pa3);
; }
; template <bool DIRECT> ...
;     ...
;         pv_d0(o, vb0 + pb_ * SHM_V, pa0, pa1, pa2, pa3); partialSM(pB0, pB1, m_reg, mnB, alB);
;         SWAIT(); SWRITE(nb_); SLOAD(j + 2);
;         RESC(alB); __syncthreads(); kb = nb_; }
	s_nop 0
	v_mfma_f32_32x32x16_bf16 v[0:15], v[150:153], v[226:229], v[0:15]
	ds_read_b64_tr_b16 v[226:227], v96 offset:0x200
	ds_read_b64_tr_b16 v[228:229], v96 offset:0xa00
	v_mfma_f32_32x32x16_bf16 v[0:15], v[168:171], v[230:233], v[0:15]
	ds_read_b64_tr_b16 v[230:231], v96 offset:0x1200
	ds_read_b64_tr_b16 v[232:233], v96 offset:0x1a00
	v_mfma_f32_32x32x16_bf16 v[0:15], v[172:175], v[234:237], v[0:15]
	ds_read_b64_tr_b16 v[234:235], v96 offset:0x2200
	ds_read_b64_tr_b16 v[236:237], v96 offset:0x2a00
	v_mfma_f32_32x32x16_bf16 v[0:15], v[222:225], v[238:241], v[0:15]
	ds_read_b64_tr_b16 v[238:239], v96 offset:0x3200
	ds_read_b64_tr_b16 v[240:241], v96 offset:0x3a00
	s_waitcnt lgkmcnt(0)
	v_mfma_f32_32x32x16_bf16 v[48:63], v[150:153], v[226:229], v[48:63]
	ds_read_b64_tr_b16 v[226:227], v96 offset:0x400
	ds_read_b64_tr_b16 v[228:229], v96 offset:0xc00
	v_mfma_f32_32x32x16_bf16 v[48:63], v[168:171], v[230:233], v[48:63]
	ds_read_b64_tr_b16 v[230:231], v96 offset:0x1400
	ds_read_b64_tr_b16 v[232:233], v96 offset:0x1c00
	v_mfma_f32_32x32x16_bf16 v[48:63], v[172:175], v[234:237], v[48:63]
	ds_read_b64_tr_b16 v[234:235], v96 offset:0x2400
	ds_read_b64_tr_b16 v[236:237], v96 offset:0x2c00
	v_mfma_f32_32x32x16_bf16 v[48:63], v[222:225], v[238:241], v[48:63]
	ds_read_b64_tr_b16 v[238:239], v96 offset:0x3400
	ds_read_b64_tr_b16 v[240:241], v96 offset:0x3c00
	s_waitcnt lgkmcnt(0)
	v_mfma_f32_32x32x16_bf16 v[32:47], v[150:153], v[226:229], v[32:47]
	ds_read_b64_tr_b16 v[226:227], v96 offset:0x600
	ds_read_b64_tr_b16 v[228:229], v96 offset:0xe00
	v_mfma_f32_32x32x16_bf16 v[32:47], v[168:171], v[230:233], v[32:47]
	ds_read_b64_tr_b16 v[230:231], v96 offset:0x1600
	ds_read_b64_tr_b16 v[232:233], v96 offset:0x1e00
	v_mfma_f32_32x32x16_bf16 v[32:47], v[172:175], v[234:237], v[32:47]
	ds_read_b64_tr_b16 v[234:235], v96 offset:0x2600
	ds_read_b64_tr_b16 v[236:237], v96 offset:0x2e00
	v_mfma_f32_32x32x16_bf16 v[32:47], v[222:225], v[238:241], v[32:47]
	ds_read_b64_tr_b16 v[238:239], v96 offset:0x3600
	ds_read_b64_tr_b16 v[240:241], v96 offset:0x3e00
	s_waitcnt lgkmcnt(0)
	v_mfma_f32_32x32x16_bf16 v[16:31], v[150:153], v[226:229], v[16:31]
	v_max_f32_e32 v96, v81, v81
	v_max_f32_e32 v150, v80, v80
	v_max_f32_e32 v96, v150, v96
	v_max3_f32 v96, v96, v82, v83
	v_max3_f32 v96, v96, v84, v85
	v_max3_f32 v96, v96, v86, v87
	v_max3_f32 v96, v96, v88, v89
	v_max3_f32 v96, v96, v90, v91
	v_max3_f32 v96, v96, v92, v93
	v_max3_f32 v96, v96, v94, v95
	v_max3_f32 v96, v96, v64, v65
	v_max3_f32 v96, v96, v66, v67
	v_max3_f32 v96, v96, v68, v69
	v_max3_f32 v96, v96, v70, v71
	v_max3_f32 v96, v96, v72, v73
	v_max3_f32 v96, v96, v74, v75
	v_max3_f32 v96, v96, v76, v77
	v_max3_f32 v96, v96, v78, v79
	v_mov_b32_e32 v150, v96
	s_nop 1
	v_permlane32_swap_b32_e32 v96, v150
	v_max_f32_e32 v150, v150, v150
	v_max_f32_e32 v96, v96, v96
	v_max_f32_e32 v96, v96, v150
	v_sub_f32_e32 v150, v96, v221
	v_cmp_ge_f32_e32 vcc, s14, v150
	s_cmp_eq_u64 vcc, exec
	s_mul_i32 s26, s56, 34
	s_cselect_b64 s[40:41], -1, 0
	s_mul_i32 s25, s23, 0x6000
	s_add_i32 s26, s26, s22
	s_lshl_b32 s24, s23, 14
	s_add_i32 s25, s25, 0
	s_add_i32 s26, s26, 2
	s_cmp_lt_u32 s26, 4
	v_add_u32_e32 v151, s24, v191
	s_cselect_b32 s26, s19, s21
	s_waitcnt vmcnt(0)
	s_waitcnt vmcnt(4)
	ds_write_b128 v151, v[130:133]
	s_waitcnt vmcnt(2)
	ds_write_b128 v151, v[134:137] offset:8192
	v_add_u32_e32 v130, s25, v188
	s_add_i32 s26, s26, s20
	s_waitcnt vmcnt(0)
	ds_write_b128 v130, v[142:145] offset:49152
	ds_write_b128 v130, v[146:149] offset:61440
	v_add_u32_e32 v130, s25, v189
	s_add_i32 s28, s26, 0xc0
	ds_write_b128 v130, v[138:141] offset:49152
	v_mad_i64_i32 v[138:139], s[26:27], s28, v220, v[164:165]
	v_add_co_u32_e32 v140, vcc, 0x1c000, v138
	global_load_dwordx4 v[130:133], v[138:139], off offset:256
	s_nop 0
	v_addc_co_u32_e32 v141, vcc, 0, v139, vcc
	global_load_dwordx4 v[134:137], v[140:141], off offset:256
	global_load_dwordx4 v[142:145], v[138:139], off
	global_load_dwordx4 v[146:149], v[140:141], off
	v_mad_i64_i32 v[138:139], s[26:27], s28, v218, v[158:159]
	global_load_dwordx4 v[138:141], v[138:139], off
	v_mfma_f32_32x32x16_bf16 v[16:31], v[168:171], v[230:233], v[16:31]
	v_max_f32_e32 v150, v221, v221
	v_max_f32_e32 v96, v150, v96
	v_sub_f32_e32 v150, v221, v96
	v_mul_f32_e32 v150, 0x3dd53b94, v150
	v_exp_f32_e32 v150, v150
	s_nop 0
	v_cndmask_b32_e64 v150, v150, 1.0, s[40:41]
	v_mfma_f32_32x32x16_bf16 v[16:31], v[172:175], v[234:237], v[16:31]
	v_cmp_gt_f32_e32 vcc, 1.0, v150
	v_mfma_f32_32x32x16_bf16 v[16:31], v[222:225], v[238:241], v[16:31]
	s_cbranch_vccz .LBB0_840
	s_and_saveexec_b64 s[46:47], s[38:39]
	ds_write_b32 v192, v150 offset:128
	s_or_b64 exec, exec, s[46:47]
	s_waitcnt lgkmcnt(0)
	v_add_u32_e32 v151, v155, v193
	ds_read_b128 v[168:171], v151 offset:224
	ds_read_b128 v[172:175], v151 offset:192
	ds_read_b128 v[222:225], v151 offset:160
	ds_read_b128 v[226:229], v151 offset:128
	s_waitcnt lgkmcnt(3)
	v_pk_mul_f32 v[12:13], v[12:13], v[168:169]
	s_waitcnt lgkmcnt(2)
	v_pk_mul_f32 v[8:9], v[8:9], v[172:173]
	s_waitcnt lgkmcnt(1)
	v_pk_mul_f32 v[4:5], v[4:5], v[222:223]
	v_pk_mul_f32 v[14:15], v[14:15], v[170:171]
	v_pk_mul_f32 v[10:11], v[10:11], v[174:175]
	v_pk_mul_f32 v[6:7], v[6:7], v[224:225]
	s_waitcnt lgkmcnt(0)
	v_pk_mul_f32 v[2:3], v[2:3], v[228:229]
	v_pk_mul_f32 v[0:1], v[0:1], v[226:227]
	v_pk_mul_f32 v[60:61], v[60:61], v[168:169]
	v_pk_mul_f32 v[56:57], v[56:57], v[172:173]
	v_pk_mul_f32 v[52:53], v[52:53], v[222:223]
	v_pk_mul_f32 v[62:63], v[62:63], v[170:171]
	v_pk_mul_f32 v[58:59], v[58:59], v[174:175]
	v_pk_mul_f32 v[54:55], v[54:55], v[224:225]
	v_pk_mul_f32 v[50:51], v[50:51], v[228:229]
	v_pk_mul_f32 v[48:49], v[48:49], v[226:227]
	v_pk_mul_f32 v[44:45], v[44:45], v[168:169]
	v_pk_mul_f32 v[40:41], v[40:41], v[172:173]
	v_pk_mul_f32 v[36:37], v[36:37], v[222:223]
	v_pk_mul_f32 v[46:47], v[46:47], v[170:171]
	v_pk_mul_f32 v[42:43], v[42:43], v[174:175]
	v_pk_mul_f32 v[38:39], v[38:39], v[224:225]
	v_pk_mul_f32 v[34:35], v[34:35], v[228:229]
	v_pk_mul_f32 v[32:33], v[32:33], v[226:227]
	v_pk_mul_f32 v[28:29], v[28:29], v[168:169]
	v_pk_mul_f32 v[24:25], v[24:25], v[172:173]
	v_pk_mul_f32 v[20:21], v[20:21], v[222:223]
	v_pk_mul_f32 v[30:31], v[30:31], v[170:171]
	v_pk_mul_f32 v[26:27], v[26:27], v[174:175]
	v_pk_mul_f32 v[22:23], v[22:23], v[224:225]
	v_pk_mul_f32 v[18:19], v[18:19], v[228:229]
	v_pk_mul_f32 v[16:17], v[16:17], v[226:227]

; #define LAS __attribute__((address_space(3)))
; #define SBAR() __builtin_amdgcn_sched_barrier(0)
; __device__ __forceinline__ void finishSM(f32x16& p0, f32x16& p1, float alpha, float& l_reg, bf16x8& pa0, bf16x8& pa1, bf16x8& pa2, bf16x8& pa3) {
; #pragma unroll
;     for (int r = 0; r < 16; ++r) p1[r] = __builtin_amdgcn_exp2f(p1[r]);
;     float ps = 0;
; #pragma unroll
;     for (int r = 0; r < 16; ++r) ps += p0[r];
; #pragma unroll
;     for (int r = 0; r < 16; ++r) ps += p1[r];
;     { auto rr = __builtin_amdgcn_permlane32_swap(__float_as_uint(ps), __float_as_uint(ps), false, false);
;       ps = __uint_as_float(rr[0]) + __uint_as_float(rr[1]); }
;     l_reg = l_reg * alpha + ps;
;     ...
;     PK4(p0, 0, pa0); PK4(p0, 8, pa1); PK4(p1, 0, pa2); PK4(p1, 8, pa3);
;     ...
; }
; __device__ __forceinline__ void qkt(f32x16& p0, f32x16& p1, const LAS unsigned char* Ks, const bf16x8* qr, const LAS unsigned char* qrp, int qsw, const int (&kq)[4], int hi) {
;     p0 = f32x16{}; p1 = f32x16{};
; #pragma unroll
;     for (int d0 = 0; d0 < 12; ++d0) {
;         const bf16x8 b0 = *(const LAS bf16x8*)(Ks + kq[d0 & 3] + 128 * (d0 >> 2));
;         const bf16x8 b1 = *(const LAS bf16x8*)(Ks + kq[d0 & 3] + 128 * (d0 >> 2) + 32 * 384);
;         bf16x8 qv; if (d0 < 8) qv = qr[d0]; else qv = *(const LAS bf16x8*)(qrp + (((2 * (d0 - 8) + hi) ^ qsw) << 4));
;         p0 = __builtin_amdgcn_mfma_f32_32x32x16_bf16(b0, qv, p0, 0, 0, 0);
;         p1 = __builtin_amdgcn_mfma_f32_32x32x16_bf16(b1, qv, p1, 0, 0, 0); }
; }
; template <bool DIRECT> ...
;     ...
;     { const int pb_ = kb == 0 ? 2 : kb - 1;
;     SBAR(); qkt(pB0, pB1, K_lds + kb * SHM_K, qr, qrp, qsw, kq, hi);
;     finishSM(pA0, pA1, alA, l_reg, pa0, pa1, pa2, pa3); SBAR();
;     pv_d0(o, vb0 + pb_ * SHM_V, pa0, pa1, pa2, pa3); partialSM(pB0, pB1, m_reg, mnB, alB);
.LBB0_848:
	s_setprio 0
	ds_read_b128 v[64:67], v209 offset:49152
	ds_read_b128 v[68:71], v209 offset:61440
	v_add_f32_e32 v96, 0, v235
	v_add_f32_e32 v96, v237, v96
	v_add_f32_e32 v96, v233, v96
	s_waitcnt lgkmcnt(1)
	v_mfma_f32_32x32x16_bf16 v[80:95], v[64:67], v[126:129], 0
	v_add_f32_e32 v96, v236, v96
	v_add_f32_e32 v96, v232, v96
	v_add_f32_e32 v96, v234, v96
	v_add_f32_e32 v96, v230, v96
	v_add_f32_e32 v96, v231, v96
	v_add_f32_e32 v96, v227, v96
	v_add_f32_e32 v96, v229, v96
	s_waitcnt lgkmcnt(0)
	v_mfma_f32_32x32x16_bf16 v[64:79], v[68:71], v[126:129], 0
	ds_read_b128 v[126:129], v211 offset:49152
	s_waitcnt vmcnt(4)
	ds_read_b128 v[130:133], v211 offset:61440
	v_add_f32_e32 v96, v226, v96
	v_add_f32_e32 v96, v228, v96
	v_add_f32_e32 v96, v223, v96
	v_add_f32_e32 v96, v225, v96
	v_add_f32_e32 v96, v222, v96
	v_add_f32_e32 v96, v224, v96
	s_waitcnt lgkmcnt(0)
	v_mfma_f32_32x32x16_bf16 v[64:79], v[130:133], v[122:125], v[64:79]
	v_mfma_f32_32x32x16_bf16 v[80:95], v[126:129], v[122:125], v[80:95]
	ds_read_b128 v[122:125], v210 offset:49152
	ds_read_b128 v[126:129], v210 offset:61440
	s_waitcnt lgkmcnt(0)
	v_mfma_f32_32x32x16_bf16 v[64:79], v[126:129], v[118:121], v[64:79]
	v_mfma_f32_32x32x16_bf16 v[80:95], v[122:125], v[118:121], v[80:95]
	ds_read_b128 v[118:121], v208 offset:49152
	ds_read_b128 v[122:125], v208 offset:61440
	s_waitcnt lgkmcnt(0)
	v_mfma_f32_32x32x16_bf16 v[64:79], v[122:125], v[114:117], v[64:79]
	v_exp_f32_e32 v122, v151
	v_mfma_f32_32x32x16_bf16 v[80:95], v[118:121], v[114:117], v[80:95]
	ds_read_b128 v[114:117], v209 offset:49280
	ds_read_b128 v[118:121], v209 offset:61568
	s_waitcnt lgkmcnt(0)
	v_mfma_f32_32x32x16_bf16 v[64:79], v[118:121], v[110:113], v[64:79]
	v_exp_f32_e32 v118, v167
	v_exp_f32_e32 v119, v152
	v_exp_f32_e32 v120, v153
	v_exp_f32_e32 v121, v150
	v_mfma_f32_32x32x16_bf16 v[80:95], v[114:117], v[110:113], v[80:95]
	ds_read_b128 v[110:113], v211 offset:49280
	ds_read_b128 v[114:117], v211 offset:61568
	s_waitcnt lgkmcnt(0)
	v_mfma_f32_32x32x16_bf16 v[64:79], v[114:117], v[106:109], v[64:79]
	v_exp_f32_e32 v114, v171
	v_exp_f32_e32 v115, v168
	v_exp_f32_e32 v116, v169
	v_exp_f32_e32 v117, v166
	v_mfma_f32_32x32x16_bf16 v[80:95], v[110:113], v[106:109], v[80:95]
	ds_read_b128 v[106:109], v210 offset:49280
	ds_read_b128 v[110:113], v210 offset:61568
	s_waitcnt lgkmcnt(0)
	v_mfma_f32_32x32x16_bf16 v[64:79], v[110:113], v[102:105], v[64:79]
	v_exp_f32_e32 v110, v175
	v_exp_f32_e32 v111, v172
	v_exp_f32_e32 v112, v173
	v_exp_f32_e32 v113, v170
	v_mfma_f32_32x32x16_bf16 v[80:95], v[106:109], v[102:105], v[80:95]
	ds_read_b128 v[102:105], v208 offset:49280
	ds_read_b128 v[106:109], v208 offset:61568
	s_waitcnt lgkmcnt(0)
	v_mfma_f32_32x32x16_bf16 v[64:79], v[106:109], v[98:101], v[64:79]
	v_mfma_f32_32x32x16_bf16 v[80:95], v[102:105], v[98:101], v[80:95]
	ds_read_b128 v[98:101], v209 offset:49408
	ds_read_b128 v[102:105], v209 offset:61696
	ds_read_b128 v[106:109], v207
	s_waitcnt lgkmcnt(0)
	v_mfma_f32_32x32x16_bf16 v[64:79], v[102:105], v[106:109], v[64:79]
	v_mfma_f32_32x32x16_bf16 v[80:95], v[98:101], v[106:109], v[80:95]
	ds_read_b128 v[98:101], v211 offset:49408
	ds_read_b128 v[102:105], v211 offset:61696
	ds_read_b128 v[106:109], v206
	s_waitcnt lgkmcnt(0)
	v_mfma_f32_32x32x16_bf16 v[64:79], v[102:105], v[106:109], v[64:79]
	v_mfma_f32_32x32x16_bf16 v[80:95], v[98:101], v[106:109], v[80:95]
	ds_read_b128 v[98:101], v210 offset:49408
	ds_read_b128 v[102:105], v210 offset:61696
	ds_read_b128 v[106:109], v197
	s_waitcnt lgkmcnt(0)
	v_mfma_f32_32x32x16_bf16 v[64:79], v[102:105], v[106:109], v[64:79]
	v_mfma_f32_32x32x16_bf16 v[80:95], v[98:101], v[106:109], v[80:95]
	ds_read_b128 v[98:101], v208 offset:49408
	ds_read_b128 v[102:105], v208 offset:61696
	ds_read_b128 v[106:109], v161
	s_waitcnt lgkmcnt(0)
	v_mfma_f32_32x32x16_bf16 v[64:79], v[102:105], v[106:109], v[64:79]
	v_exp_f32_e32 v103, v176
	s_nop 0
	v_add_f32_e32 v96, v103, v96
	v_mfma_f32_32x32x16_bf16 v[80:95], v[98:101], v[106:109], v[80:95]
	v_exp_f32_e32 v108, v177
	v_exp_f32_e32 v109, v174
	v_cvt_pk_bf16_f32 v98, v235, v237
	v_cvt_pk_bf16_f32 v99, v233, v236
	v_add_f32_e32 v96, v108, v96
	v_add_f32_e32 v96, v109, v96
	v_add_f32_e32 v96, v110, v96
	v_add_f32_e32 v96, v111, v96
	v_add_f32_e32 v96, v112, v96
	v_add_f32_e32 v96, v113, v96
	v_add_f32_e32 v96, v114, v96
	v_add_f32_e32 v96, v115, v96
	v_add_f32_e32 v96, v116, v96
	v_add_f32_e32 v96, v117, v96
	v_add_f32_e32 v96, v118, v96
	v_add_f32_e32 v96, v119, v96
	v_add_f32_e32 v96, v120, v96
	v_add_f32_e32 v96, v121, v96
	v_add_f32_e32 v96, v122, v96
	v_mov_b32_e32 v102, v96
	v_cvt_pk_bf16_f32 v100, v232, v234
	v_cvt_pk_bf16_f32 v101, v230, v231
	s_nop 1
	v_permlane32_swap_b32_e32 v96, v102
	v_permlane32_swap_b32_e32 v98, v100
	v_permlane32_swap_b32_e32 v99, v101
	v_cvt_pk_bf16_f32 v104, v227, v229
	v_cvt_pk_bf16_f32 v105, v226, v228
	v_cvt_pk_bf16_f32 v106, v223, v225
	v_cvt_pk_bf16_f32 v107, v222, v224
	v_cvt_pk_bf16_f32 v108, v103, v108
	v_cvt_pk_bf16_f32 v109, v109, v110
	v_cvt_pk_bf16_f32 v110, v111, v112
	v_cvt_pk_bf16_f32 v111, v113, v114
	v_cvt_pk_bf16_f32 v112, v115, v116
	v_cvt_pk_bf16_f32 v113, v117, v118
	v_cvt_pk_bf16_f32 v114, v119, v120
	v_cvt_pk_bf16_f32 v115, v121, v122
	s_nop 0
	v_permlane32_swap_b32_e32 v104, v106
	v_permlane32_swap_b32_e32 v105, v107
	v_permlane32_swap_b32_e32 v108, v110
	v_permlane32_swap_b32_e32 v109, v111
	v_permlane32_swap_b32_e32 v112, v114
	v_permlane32_swap_b32_e32 v113, v115
	ds_read_b64_tr_b16 v[116:117], v194 offset:0
	ds_read_b64_tr_b16 v[118:119], v194 offset:0x800
	ds_read_b64_tr_b16 v[120:121], v194 offset:0x1000
	ds_read_b64_tr_b16 v[122:123], v194 offset:0x1800
	ds_read_b64_tr_b16 v[124:125], v194 offset:0x2000
	ds_read_b64_tr_b16 v[126:127], v194 offset:0x2800
	ds_read_b64_tr_b16 v[128:129], v194 offset:0x3000
	ds_read_b64_tr_b16 v[130:131], v194 offset:0x3800
	s_waitcnt lgkmcnt(0)
; #define SBAR() __builtin_amdgcn_sched_barrier(0)
; #define RESC(a) do { if (__any((a) < 1.f)) { if (hi == 0) al_l[r32] = (a); asm volatile("s_waitcnt lgkmcnt(0)" ::: "memory"); \
;     _Pragma("unroll") for (int d = 0; d < 4; ++d) _Pragma("unroll") for (int r = 0; r < 16; ++r) o[d][r] *= al_l[crow(r, hi)]; } } while (0)
; __device__ __forceinline__ void partialSM(f32x16& p0, f32x16& p1, float& m_reg, float& mn, float& alpha) {
;     constexpr float C = SCALE * 1.4426950408889634f;
;     float pmax = p0[0];
; #pragma unroll
;     for (int r = 1; r < 16; ++r) pmax = fmaxf(pmax, p0[r]);
; #pragma unroll
;     for (int r = 0; r < 16; ++r) pmax = fmaxf(pmax, p1[r]);
;     { auto rr = __builtin_amdgcn_permlane32_swap(__float_as_uint(pmax), __float_as_uint(pmax), false, false);
;       pmax = fmaxf(__uint_as_float(rr[0]), __uint_as_float(rr[1])); }
;     if (__builtin_expect(__all(pmax - m_reg <= THR / SCALE), 1)) { mn = m_reg; alpha = 1.f; }
;     else { mn = fmaxf(m_reg, pmax); alpha = __builtin_amdgcn_exp2f((m_reg - mn) * C); m_reg = mn; }
; template <int D0> __device__ __forceinline__ void pv_one(f32x16& od, int vb, bf16x8 pa0, bf16x8 pa1, bf16x8 pa2, bf16x8 pa3) {
;     const s16x4 l0 = tr_read<v_rd_off(D0, 0, 0)>(vb), h0 = tr_read<v_rd_off(D0, 0, 1)>(vb), l1 = tr_read<v_rd_off(D0, 1, 0)>(vb), h1 = tr_read<v_rd_off(D0, 1, 1)>(vb);
;     const s16x4 l2 = tr_read<v_rd_off(D0, 2, 0)>(vb), h2 = tr_read<v_rd_off(D0, 2, 1)>(vb), l3 = tr_read<v_rd_off(D0, 3, 0)>(vb), h3 = tr_read<v_rd_off(D0, 3, 1)>(vb);
;     asm volatile("s_waitcnt lgkmcnt(0)" ::: "memory"); SBAR();
;     ...
;     od = __builtin_amdgcn_mfma_f32_32x32x16_bf16(pa0, PK(l0, h0), od, 0, 0, 0);
;     od = __builtin_amdgcn_mfma_f32_32x32x16_bf16(pa1, PK(l1, h1), od, 0, 0, 0);
;     od = __builtin_amdgcn_mfma_f32_32x32x16_bf16(pa2, PK(l2, h2), od, 0, 0, 0);
;     od = __builtin_amdgcn_mfma_f32_32x32x16_bf16(pa3, PK(l3, h3), od, 0, 0, 0);
;     ...
; }
; __device__ __forceinline__ void pv_d0(f32x16* o, int vb, bf16x8 pa0, bf16x8 pa1, bf16x8 pa2, bf16x8 pa3) {
;     pv_one<0>(o[0], vb, pa0, pa1, pa2, pa3); pv_one<1>(o[1], vb, pa0, pa1, pa2, pa3); pv_one<2>(o[2], vb, pa0, pa1, pa2, pa3); pv_one<3>(o[3], vb, pa0, pa1, pa2, pa3);
; }
; template <bool DIRECT> ...
;     ...
;     pv_d0(o, vb0 + pb_ * SHM_V, pa0, pa1, pa2, pa3); partialSM(pB0, pB1, m_reg, mnB, alB);
;     RESC(alB);
	s_nop 0
	v_mfma_f32_32x32x16_bf16 v[0:15], v[98:101], v[116:119], v[0:15]
	ds_read_b64_tr_b16 v[116:117], v194 offset:0x200
	ds_read_b64_tr_b16 v[118:119], v194 offset:0xa00
	v_mfma_f32_32x32x16_bf16 v[0:15], v[104:107], v[120:123], v[0:15]
	ds_read_b64_tr_b16 v[120:121], v194 offset:0x1200
	ds_read_b64_tr_b16 v[122:123], v194 offset:0x1a00
	v_mfma_f32_32x32x16_bf16 v[0:15], v[108:111], v[124:127], v[0:15]
	ds_read_b64_tr_b16 v[124:125], v194 offset:0x2200
	ds_read_b64_tr_b16 v[126:127], v194 offset:0x2a00
	v_mfma_f32_32x32x16_bf16 v[0:15], v[112:115], v[128:131], v[0:15]
	ds_read_b64_tr_b16 v[128:129], v194 offset:0x3200
	ds_read_b64_tr_b16 v[130:131], v194 offset:0x3a00
	s_waitcnt lgkmcnt(0)
	v_mfma_f32_32x32x16_bf16 v[48:63], v[98:101], v[116:119], v[48:63]
	ds_read_b64_tr_b16 v[116:117], v194 offset:0x400
	ds_read_b64_tr_b16 v[118:119], v194 offset:0xc00
	v_mfma_f32_32x32x16_bf16 v[48:63], v[104:107], v[120:123], v[48:63]
	ds_read_b64_tr_b16 v[120:121], v194 offset:0x1400
	ds_read_b64_tr_b16 v[122:123], v194 offset:0x1c00
	v_mfma_f32_32x32x16_bf16 v[48:63], v[108:111], v[124:127], v[48:63]
	ds_read_b64_tr_b16 v[124:125], v194 offset:0x2400
	ds_read_b64_tr_b16 v[126:127], v194 offset:0x2c00
	v_mfma_f32_32x32x16_bf16 v[48:63], v[112:115], v[128:131], v[48:63]
	ds_read_b64_tr_b16 v[128:129], v194 offset:0x3400
	ds_read_b64_tr_b16 v[130:131], v194 offset:0x3c00
	s_waitcnt lgkmcnt(0)
	v_mfma_f32_32x32x16_bf16 v[32:47], v[98:101], v[116:119], v[32:47]
	ds_read_b64_tr_b16 v[116:117], v194 offset:0x600
	ds_read_b64_tr_b16 v[118:119], v194 offset:0xe00
	v_mfma_f32_32x32x16_bf16 v[32:47], v[104:107], v[120:123], v[32:47]
	ds_read_b64_tr_b16 v[120:121], v194 offset:0x1600
	ds_read_b64_tr_b16 v[122:123], v194 offset:0x1e00
	v_mfma_f32_32x32x16_bf16 v[32:47], v[108:111], v[124:127], v[32:47]
	ds_read_b64_tr_b16 v[124:125], v194 offset:0x2600
	ds_read_b64_tr_b16 v[126:127], v194 offset:0x2e00
	v_mfma_f32_32x32x16_bf16 v[32:47], v[112:115], v[128:131], v[32:47]
	ds_read_b64_tr_b16 v[128:129], v194 offset:0x3600
	ds_read_b64_tr_b16 v[130:131], v194 offset:0x3e00
	s_waitcnt lgkmcnt(0)
	v_mfma_f32_32x32x16_bf16 v[16:31], v[98:101], v[116:119], v[16:31]
	v_max_f32_e32 v98, v81, v81
	v_max_f32_e32 v99, v80, v80
	v_max_f32_e32 v98, v99, v98
	v_max3_f32 v98, v98, v82, v83
	v_max3_f32 v98, v98, v84, v85
	v_max3_f32 v98, v98, v86, v87
	v_max3_f32 v98, v98, v88, v89
	v_max3_f32 v98, v98, v90, v91
	v_max3_f32 v98, v98, v92, v93
	v_mfma_f32_32x32x16_bf16 v[16:31], v[104:107], v[120:123], v[16:31]
	v_max3_f32 v98, v98, v94, v95
	v_max3_f32 v98, v98, v64, v65
	v_max3_f32 v98, v98, v66, v67
	v_max3_f32 v98, v98, v68, v69
	v_max3_f32 v98, v98, v70, v71
	v_max3_f32 v98, v98, v72, v73
	v_max3_f32 v98, v98, v74, v75
	v_max3_f32 v98, v98, v76, v77
	v_mfma_f32_32x32x16_bf16 v[16:31], v[108:111], v[124:127], v[16:31]
	v_max3_f32 v98, v98, v78, v79
	v_mov_b32_e32 v99, v98
	s_nop 1
	v_permlane32_swap_b32_e32 v98, v99
	v_max_f32_e32 v99, v99, v99
	v_max_f32_e32 v98, v98, v98
	v_max_f32_e32 v98, v98, v99
	v_sub_f32_e32 v99, v98, v221
	v_cmp_ge_f32_e32 vcc, s14, v99
	v_max_f32_e32 v99, v221, v221
	v_max_f32_e32 v98, v99, v98
	v_mfma_f32_32x32x16_bf16 v[16:31], v[112:115], v[128:131], v[16:31]
	v_sub_f32_e32 v99, v221, v98
	v_mul_f32_e32 v99, 0x3dd53b94, v99
	v_exp_f32_e32 v99, v99
	s_cmp_eq_u64 vcc, exec
	s_cselect_b64 s[40:41], -1, 0
	v_cndmask_b32_e64 v99, v99, 1.0, s[40:41]
	v_cmp_gt_f32_e32 vcc, 1.0, v99
	s_cbranch_vccz .LBB0_852
	s_and_saveexec_b64 s[46:47], s[38:39]
	ds_write_b32 v192, v99 offset:128
	s_or_b64 exec, exec, s[46:47]
	s_waitcnt lgkmcnt(0)
	v_add_u32_e32 v100, v155, v193
	ds_read_b128 v[104:107], v100 offset:224
	ds_read_b128 v[108:111], v100 offset:192
	ds_read_b128 v[112:115], v100 offset:160
	ds_read_b128 v[116:119], v100 offset:128
	s_waitcnt lgkmcnt(3)
	v_pk_mul_f32 v[12:13], v[12:13], v[104:105]
	s_waitcnt lgkmcnt(2)
	v_pk_mul_f32 v[8:9], v[8:9], v[108:109]
	s_waitcnt lgkmcnt(1)
	v_pk_mul_f32 v[4:5], v[4:5], v[112:113]
	v_pk_mul_f32 v[14:15], v[14:15], v[106:107]
	v_pk_mul_f32 v[10:11], v[10:11], v[110:111]
	v_pk_mul_f32 v[6:7], v[6:7], v[114:115]
	s_waitcnt lgkmcnt(0)
	v_pk_mul_f32 v[2:3], v[2:3], v[118:119]
	v_pk_mul_f32 v[0:1], v[0:1], v[116:117]
	v_pk_mul_f32 v[60:61], v[60:61], v[104:105]
	v_pk_mul_f32 v[56:57], v[56:57], v[108:109]
	v_pk_mul_f32 v[52:53], v[52:53], v[112:113]
	v_pk_mul_f32 v[62:63], v[62:63], v[106:107]
	v_pk_mul_f32 v[58:59], v[58:59], v[110:111]
	v_pk_mul_f32 v[54:55], v[54:55], v[114:115]
	v_pk_mul_f32 v[50:51], v[50:51], v[118:119]
	v_pk_mul_f32 v[48:49], v[48:49], v[116:117]
	v_pk_mul_f32 v[44:45], v[44:45], v[104:105]
	v_pk_mul_f32 v[40:41], v[40:41], v[108:109]
	v_pk_mul_f32 v[36:37], v[36:37], v[112:113]
	v_pk_mul_f32 v[46:47], v[46:47], v[106:107]
	v_pk_mul_f32 v[42:43], v[42:43], v[110:111]
	v_pk_mul_f32 v[38:39], v[38:39], v[114:115]
	v_pk_mul_f32 v[34:35], v[34:35], v[118:119]
	v_pk_mul_f32 v[32:33], v[32:33], v[116:117]
	v_pk_mul_f32 v[28:29], v[28:29], v[104:105]
	v_pk_mul_f32 v[24:25], v[24:25], v[108:109]
	v_pk_mul_f32 v[20:21], v[20:21], v[112:113]
	v_pk_mul_f32 v[30:31], v[30:31], v[106:107]
	v_pk_mul_f32 v[26:27], v[26:27], v[110:111]
	v_pk_mul_f32 v[22:23], v[22:23], v[114:115]
	v_pk_mul_f32 v[18:19], v[18:19], v[118:119]
	v_pk_mul_f32 v[16:17], v[16:17], v[116:117]
